# v104 + grid barrier: workgroups that are not their XCD's last arrival spin on the top-level generation word directly instead of the per-XCD relay word (one hop less per barrier)
# speedup vs baseline: 1.0113x; 1.0086x over previous
; __device__ __forceinline__ unsigned xb_ld(unsigned* p)              { return __hip_atomic_load(p, __ATOMIC_RELAXED, __HIP_MEMORY_SCOPE_AGENT); }
; __device__ __forceinline__ unsigned xb_add(unsigned* p, unsigned v) { return __hip_atomic_fetch_add(p, v, __ATOMIC_RELAXED, __HIP_MEMORY_SCOPE_AGENT); }
; #define XB_SPIN(cond, bar) do { unsigned _sp = 0; while (cond) { __builtin_amdgcn_s_sleep(1); \
;     if ((++_sp & 255u) == 0u) { if (xb_ld(&(bar)[XB_TMO])) break; if (_sp > XB_SPIN_CAP) { atomicAdd(&(bar)[XB_TMO], 1u); break; } } } } while (0)
; __device__ __forceinline__ void xcd_barrier(const XcdBarrier& b) {
;     ...
;         const unsigned old = xb_add(&bar[XB_XSUB(b.x)], 1u);
;         const unsigned gen = old / nloc;
;         if (old + 1u == (gen + 1u) * nloc) {
;             __builtin_amdgcn_fence(__ATOMIC_RELEASE, "agent");
;             asm volatile("s_waitcnt vmcnt(0)" ::: "memory");
;             const unsigned og = xb_add(&bar[XB_TOP], 1u);
;             const unsigned tg = og / nx;
;             if (og + 1u == (tg + 1u) * nx) xb_add(&bar[XB_TOPGEN], 1u);
;             else XB_SPIN(xb_ld(&bar[XB_TOPGEN]) == tg, bar);
;             __builtin_amdgcn_fence(__ATOMIC_ACQUIRE, "agent");
;             xb_add(&bar[XB_XGEN(b.x)], 1u);
;             asm volatile("s_waitcnt vmcnt(0)" ::: "memory");
;         } else {
;             XB_SPIN(xb_ld(&bar[XB_XGEN(b.x)]) == gen, bar);
.LBB0_1219:
	s_or_b64 exec, exec, s[20:21]
	v_cvt_f32_u32_e32 v5, v3
	s_waitcnt vmcnt(0)
	v_readfirstlane_b32 s20, v4
	v_sub_u32_e32 v4, 0, v3
	v_rcp_iflag_f32_e32 v5, v5
	v_add_u32_e32 v6, s20, v0
	v_mul_f32_e32 v5, 0x4f7ffffe, v5
	v_cvt_u32_f32_e32 v5, v5
	v_mul_lo_u32 v0, v4, v5
	v_mul_hi_u32 v0, v5, v0
	v_add_u32_e32 v0, v5, v0
	v_mul_hi_u32 v0, v6, v0
	v_mul_lo_u32 v4, v0, v3
	v_sub_u32_e32 v4, v6, v4
	v_add_u32_e32 v5, 1, v0
	v_cmp_ge_u32_e32 vcc, v4, v3
	s_nop 1
	v_cndmask_b32_e32 v0, v0, v5, vcc
	v_sub_u32_e32 v5, v4, v3
	v_cndmask_b32_e32 v4, v4, v5, vcc
	v_add_u32_e32 v5, 1, v0
	v_cmp_ge_u32_e32 vcc, v4, v3
	v_add_u32_e32 v4, 1, v6
	s_nop 0
	v_cndmask_b32_e32 v0, v0, v5, vcc
	v_mul_lo_u32 v5, v3, v0
	v_add_u32_e32 v3, v5, v3
	v_cmp_ne_u32_e32 vcc, v4, v3
	s_and_saveexec_b64 s[20:21], vcc
	s_xor_b64 s[20:21], exec, s[20:21]
	s_cbranch_execz .LBB0_1233
	v_readlane_b32 s22, v252, 27
	v_readlane_b32 s23, v252, 28
	s_waitcnt lgkmcnt(0)
	s_nop 3
	global_load_dword v2, v1, s[22:23] sc1
	s_waitcnt vmcnt(0)
	v_cmp_eq_u32_e32 vcc, v2, v0
	s_and_saveexec_b64 s[22:23], vcc
	s_cbranch_execz .LBB0_1232
	s_mov_b32 s30, 1
	s_mov_b64 s[24:25], 0
	s_branch .LBB0_1223
